# K-loops: merged pre-barrier waits, dropped redundant lgkmcnt(0), loop heads 64-byte aligned
# speedup vs baseline: 1.0025x; 1.0025x over previous
; template <class Epi, class Sched, bool ALIGN_EPI = false, bool SP2 = false>
; __device__ __forceinline__ void gemm_phase(PG8_LAS unsigned char* lds, const Gemm g, const Sched& S, const Epi& E, int wave_in) {
;     ...
;         const bool has_next = S.next(ui + 1, nxt);
;         const char* nA = has_next ? (const char*)g.A + (size_t)nxt.pm * tstepA : cA; const char* nB = has_next ? (const char*)g.Bt + (size_t)nxt.pn * tstep : cB;
;     ...
; #pragma unroll
;         for (int a = 0; a < 2; ++a)
; #pragma unroll
;             for (int b = 0; b < 2; ++b)
; #pragma unroll
;                 for (int m = 0; m < 4; ++m)
; #pragma unroll
;                     for (int n = 0; n < 2; ++n) acc[a][b][m][n] = (f32x4){0.f, 0.f, 0.f, 0.f};
;         cur = nxt; cA = nA; cB = nB; ++ui;
.LBB0_106:
	s_ashr_i32 s21, s20, 31
	s_lshl_b64 s[22:23], s[20:21], 20
	s_add_u32 s22, s36, s22
	s_addc_u32 s23, s37, s23
	s_and_b64 s[24:25], s[4:5], exec
	s_cselect_b32 s21, s23, s27
	s_cselect_b32 s50, s22, s26
	s_ashr_i32 s19, s18, 31
	s_lshl_b64 s[24:25], s[18:19], 18
	s_add_u32 s24, s38, s24
	s_addc_u32 s25, s39, s25
	s_and_b64 s[30:31], s[4:5], exec
	s_cselect_b32 s19, s25, s29
	s_cselect_b32 s51, s24, s28
	s_add_u32 s26, s26, 0x80080
	s_addc_u32 s27, s27, 0
	s_add_u32 s52, s28, 0x100
	v_mov_b32_e32 v2, 0
	s_addc_u32 s53, s29, 0
	s_mov_b32 s54, -2
	v_mov_b32_e32 v3, v2
	v_mov_b32_e32 v4, v2
	v_mov_b32_e32 v5, v2
	v_mov_b32_e32 v6, v2
	v_mov_b32_e32 v7, v2
	v_mov_b32_e32 v8, v2
	v_mov_b32_e32 v9, v2
	v_mov_b32_e32 v18, v2
	v_mov_b32_e32 v19, v2
	s_waitcnt vmcnt(0)
	v_mov_b32_e32 v20, v2
	v_mov_b32_e32 v21, v2
	v_mov_b32_e32 v22, v2
	v_mov_b32_e32 v23, v2
	v_mov_b32_e32 v24, v2
	v_mov_b32_e32 v25, v2
	v_mov_b32_e32 v34, v2
	v_mov_b32_e32 v35, v2
	v_mov_b32_e32 v36, v2
	v_mov_b32_e32 v37, v2
	v_mov_b32_e32 v38, v2
	v_mov_b32_e32 v39, v2
	v_mov_b32_e32 v40, v2
	v_mov_b32_e32 v41, v2
	v_mov_b32_e32 v50, v2
	v_mov_b32_e32 v51, v2
	v_mov_b32_e32 v52, v2
	v_mov_b32_e32 v53, v2
	v_mov_b32_e32 v54, v2
	v_mov_b32_e32 v55, v2
	v_mov_b32_e32 v56, v2
	v_mov_b32_e32 v57, v2
	v_mov_b32_e32 v10, v2
	v_mov_b32_e32 v11, v2
	v_mov_b32_e32 v12, v2
	v_mov_b32_e32 v13, v2
	v_mov_b32_e32 v14, v2
	v_mov_b32_e32 v15, v2
	v_mov_b32_e32 v16, v2
	v_mov_b32_e32 v17, v2
	v_mov_b32_e32 v26, v2
	v_mov_b32_e32 v27, v2
	v_mov_b32_e32 v28, v2
	v_mov_b32_e32 v29, v2
	v_mov_b32_e32 v30, v2
	v_mov_b32_e32 v31, v2
	v_mov_b32_e32 v32, v2
	v_mov_b32_e32 v33, v2
	v_mov_b32_e32 v42, v2
	v_mov_b32_e32 v43, v2
	v_mov_b32_e32 v44, v2
	v_mov_b32_e32 v45, v2
	v_mov_b32_e32 v46, v2
	v_mov_b32_e32 v47, v2
	v_mov_b32_e32 v48, v2
	v_mov_b32_e32 v49, v2
	v_mov_b32_e32 v58, v2
	v_mov_b32_e32 v59, v2
	v_mov_b32_e32 v60, v2
	v_mov_b32_e32 v61, v2
	v_mov_b32_e32 v62, v2
	v_mov_b32_e32 v63, v2
	v_mov_b32_e32 v64, v2
	v_mov_b32_e32 v65, v2
	v_mov_b32_e32 v66, v2
	v_mov_b32_e32 v67, v2
	v_mov_b32_e32 v68, v2
	v_mov_b32_e32 v69, v2
	v_mov_b32_e32 v70, v2
	v_mov_b32_e32 v71, v2
	v_mov_b32_e32 v72, v2
	v_mov_b32_e32 v73, v2
	v_mov_b32_e32 v82, v2
	v_mov_b32_e32 v83, v2
	v_mov_b32_e32 v84, v2
	v_mov_b32_e32 v85, v2
	v_mov_b32_e32 v86, v2
	v_mov_b32_e32 v87, v2
	v_mov_b32_e32 v88, v2
	v_mov_b32_e32 v89, v2
	v_mov_b32_e32 v98, v2
	v_mov_b32_e32 v99, v2
	v_mov_b32_e32 v100, v2
	v_mov_b32_e32 v101, v2
	v_mov_b32_e32 v102, v2
	v_mov_b32_e32 v103, v2
	v_mov_b32_e32 v104, v2
	v_mov_b32_e32 v105, v2
	v_mov_b32_e32 v114, v2
	v_mov_b32_e32 v115, v2
	v_mov_b32_e32 v116, v2
	v_mov_b32_e32 v117, v2
	v_mov_b32_e32 v118, v2
	v_mov_b32_e32 v119, v2
	v_mov_b32_e32 v120, v2
	v_mov_b32_e32 v121, v2
	v_mov_b32_e32 v74, v2
	v_mov_b32_e32 v75, v2
	v_mov_b32_e32 v76, v2
	v_mov_b32_e32 v77, v2
	v_mov_b32_e32 v78, v2
	v_mov_b32_e32 v79, v2
	v_mov_b32_e32 v80, v2
	v_mov_b32_e32 v81, v2
	v_mov_b32_e32 v90, v2
	v_mov_b32_e32 v91, v2
	v_mov_b32_e32 v92, v2
	v_mov_b32_e32 v93, v2
	v_mov_b32_e32 v94, v2
	v_mov_b32_e32 v95, v2
	v_mov_b32_e32 v96, v2
	v_mov_b32_e32 v97, v2
	v_mov_b32_e32 v106, v2
	v_mov_b32_e32 v107, v2
	v_mov_b32_e32 v108, v2
	v_mov_b32_e32 v109, v2
	v_mov_b32_e32 v110, v2
	v_mov_b32_e32 v111, v2
	v_mov_b32_e32 v112, v2
	v_mov_b32_e32 v113, v2
	v_mov_b32_e32 v122, v2
	v_mov_b32_e32 v123, v2
	v_mov_b32_e32 v124, v2
	v_mov_b32_e32 v125, v2
	v_mov_b32_e32 v126, v2
	v_mov_b32_e32 v127, v2
	v_mov_b32_e32 v128, v2
	v_mov_b32_e32 v129, v2
	s_nop 0
	s_nop 0
	s_nop 0
	s_nop 0
	s_nop 0
	s_nop 0
	s_nop 0
	s_nop 0
	s_nop 0
	s_nop 0
	s_nop 0

; template <class Epi, class Sched, bool ALIGN_EPI = false, bool SP2 = false>
; __device__ __forceinline__ void gemm_phase(PG8_LAS unsigned char* lds, const Gemm g, const Sched& S, const Epi& E, int wave_in) {
;     ...
; #pragma unroll
;         for (int a = 0; a < 2; ++a)
; #pragma unroll
;             for (int b = 0; b < 2; ++b)
; #pragma unroll
;                 for (int m = 0; m < 4; ++m)
; #pragma unroll
;                     for (int n = 0; n < 2; ++n) acc[a][b][m][n] = (f32x4){0.f, 0.f, 0.f, 0.f};
;         cur = nxt; cA = nA; cB = nB; ++ui;
.LBB0_403:
	s_add_u32 s4, s24, 0x80
	s_addc_u32 s5, s25, 0
	s_add_u32 s24, s6, 0x100
	v_mov_b32_e32 v2, 0
	s_addc_u32 s25, s7, 0
	s_mov_b32 s6, 0
	v_mov_b32_e32 v3, v2
	v_mov_b32_e32 v4, v2
	v_mov_b32_e32 v5, v2
	v_mov_b32_e32 v6, v2
	s_waitcnt lgkmcnt(0)
	v_mov_b32_e32 v7, v2
	v_mov_b32_e32 v8, v2
	v_mov_b32_e32 v9, v2
	v_mov_b32_e32 v18, v2
	v_mov_b32_e32 v19, v2
	v_mov_b32_e32 v20, v2
	v_mov_b32_e32 v21, v2
	v_mov_b32_e32 v22, v2
	v_mov_b32_e32 v23, v2
	s_waitcnt vmcnt(0)
	v_mov_b32_e32 v24, v2
	v_mov_b32_e32 v25, v2
	v_mov_b32_e32 v34, v2
	v_mov_b32_e32 v35, v2
	v_mov_b32_e32 v36, v2
	v_mov_b32_e32 v37, v2
	v_mov_b32_e32 v38, v2
	v_mov_b32_e32 v39, v2
	v_mov_b32_e32 v40, v2
	v_mov_b32_e32 v41, v2
	v_mov_b32_e32 v50, v2
	v_mov_b32_e32 v51, v2
	v_mov_b32_e32 v52, v2
	v_mov_b32_e32 v53, v2
	v_mov_b32_e32 v54, v2
	v_mov_b32_e32 v55, v2
	v_mov_b32_e32 v56, v2
	v_mov_b32_e32 v57, v2
	v_mov_b32_e32 v10, v2
	v_mov_b32_e32 v11, v2
	v_mov_b32_e32 v12, v2
	v_mov_b32_e32 v13, v2
	v_mov_b32_e32 v14, v2
	v_mov_b32_e32 v15, v2
	v_mov_b32_e32 v16, v2
	v_mov_b32_e32 v17, v2
	v_mov_b32_e32 v26, v2
	v_mov_b32_e32 v27, v2
	v_mov_b32_e32 v28, v2
	v_mov_b32_e32 v29, v2
	v_mov_b32_e32 v30, v2
	v_mov_b32_e32 v31, v2
	v_mov_b32_e32 v32, v2
	v_mov_b32_e32 v33, v2
	v_mov_b32_e32 v42, v2
	v_mov_b32_e32 v43, v2
	v_mov_b32_e32 v44, v2
	v_mov_b32_e32 v45, v2
	v_mov_b32_e32 v46, v2
	v_mov_b32_e32 v47, v2
	v_mov_b32_e32 v48, v2
	v_mov_b32_e32 v49, v2
	v_mov_b32_e32 v58, v2
	v_mov_b32_e32 v59, v2
	v_mov_b32_e32 v60, v2
	v_mov_b32_e32 v61, v2
	v_mov_b32_e32 v62, v2
	v_mov_b32_e32 v63, v2
	v_mov_b32_e32 v64, v2
	v_mov_b32_e32 v65, v2
	v_mov_b32_e32 v66, v2
	v_mov_b32_e32 v67, v2
	v_mov_b32_e32 v68, v2
	v_mov_b32_e32 v69, v2
	v_mov_b32_e32 v70, v2
	v_mov_b32_e32 v71, v2
	v_mov_b32_e32 v72, v2
	v_mov_b32_e32 v73, v2
	v_mov_b32_e32 v82, v2
	v_mov_b32_e32 v83, v2
	v_mov_b32_e32 v84, v2
	v_mov_b32_e32 v85, v2
	v_mov_b32_e32 v86, v2
	v_mov_b32_e32 v87, v2
	v_mov_b32_e32 v88, v2
	v_mov_b32_e32 v89, v2
	v_mov_b32_e32 v98, v2
	v_mov_b32_e32 v99, v2
	v_mov_b32_e32 v100, v2
	v_mov_b32_e32 v101, v2
	v_mov_b32_e32 v102, v2
	v_mov_b32_e32 v103, v2
	v_mov_b32_e32 v104, v2
	v_mov_b32_e32 v105, v2
	v_mov_b32_e32 v114, v2
	v_mov_b32_e32 v115, v2
	v_mov_b32_e32 v116, v2
	v_mov_b32_e32 v117, v2
	v_mov_b32_e32 v118, v2
	v_mov_b32_e32 v119, v2
	v_mov_b32_e32 v120, v2
	v_mov_b32_e32 v121, v2
	v_mov_b32_e32 v74, v2
	v_mov_b32_e32 v75, v2
	v_mov_b32_e32 v76, v2
	v_mov_b32_e32 v77, v2
	v_mov_b32_e32 v78, v2
	v_mov_b32_e32 v79, v2
	v_mov_b32_e32 v80, v2
	v_mov_b32_e32 v81, v2
	v_mov_b32_e32 v90, v2
	v_mov_b32_e32 v91, v2
	v_mov_b32_e32 v92, v2
	v_mov_b32_e32 v93, v2
	v_mov_b32_e32 v94, v2
	v_mov_b32_e32 v95, v2
	v_mov_b32_e32 v96, v2
	v_mov_b32_e32 v97, v2
	v_mov_b32_e32 v106, v2
	v_mov_b32_e32 v107, v2
	v_mov_b32_e32 v108, v2
	v_mov_b32_e32 v109, v2
	v_mov_b32_e32 v110, v2
	v_mov_b32_e32 v111, v2
	v_mov_b32_e32 v112, v2
	v_mov_b32_e32 v113, v2
	v_mov_b32_e32 v122, v2
	v_mov_b32_e32 v123, v2
	v_mov_b32_e32 v124, v2
	v_mov_b32_e32 v125, v2
	v_mov_b32_e32 v126, v2
	v_mov_b32_e32 v127, v2
	v_mov_b32_e32 v128, v2
	v_mov_b32_e32 v129, v2
	s_nop 0
.LBB0_404:
	s_cmp_eq_u32 s100, 1
	s_cbranch_scc0 .Lmg_nohook
	s_cmp_eq_u32 s6, 16
	s_cbranch_scc1 .Lmg_rescale01
	s_cmp_eq_u32 s6, 24
	s_cbranch_scc1 .Lmg_rescale12
